# P5: while the forward substitution runs (memory idle) each thread touches one line of the next unit's q/k/v rows so the next unit's conv loads hit L2
# speedup vs baseline: 1.0045x; 1.0033x over previous
; __device__ __forceinline__ void prep_unit(const int PREP_STEPS, LAS unsigned char* lds, int uidx, bf16* Qg, bf16* Kg, bf16* Vg, bf16* KT, bf16* QK, const bf16* HALO, const float* wconv, const float* BETA, const float* GG, float* GC) {
;     ...
;             for (int i = 0; i < 7; ++i) { const int rr = 4 * rg - 3 + i; u32x4 w = (u32x4){0u, 0u, 0u, 0u};
;                 if (rr >= 0) w = *(const u32x4*)(src + (size_t)(m0 + rr) * D + colh);
;     ...
;     if (PREP_STEPS & 4) {
;         const bool active = hb == 0 ? (tl < 128) : (tl >= 128);
;         if (active) {
;         const int c = tl & 127;
;         bf16* dstu = Vg + (size_t)m0 * D + h * 128 + c; bf16* dstw = Kg + (size_t)m0 * D + h * 128 + c;
; #pragma unroll 1
;         for (int I = 0; I < 4; ++I) {
.LBB0_762:
	s_waitcnt lgkmcnt(0)
	s_barrier
	s_mov_b64 s[6:7], exec
	s_and_b64 s[0:1], s[4:5], exec
	s_cmp_lg_u64 s[0:1], 0
	s_cselect_b32 s12, s10, s8
	s_cselect_b32 s13, s11, s9
	s_mov_b32 s14, 0x4400
	s_cselect_b32 s14, 0x8800, s14
	s_mov_b32 s15, 0x11200
	s_cselect_b32 s15, 0x11100, s15
	s_lshl_b32 s0, s82, 8
	s_add_u32 s12, s12, s0
	s_addc_u32 s13, s13, 0
	v_lshlrev_b32_e32 v16, 1, v56
	v_add_u32_e32 v16, v16, v110
	v_add_u32_e32 v16, s14, v16
	v_mov_b32_e32 v17, v16
	v_add_u32_e32 v48, s15, v110
	v_and_b32_e32 v49, 3, v154
	v_lshlrev_b32_e32 v49, 4, v49
	v_add_u32_e32 v49, v49, v110
	v_add_u32_e32 v49, 0xcc00, v49
	s_mov_b32 s1, 0
	v_and_b32_e32 v240, 0x7f, v154
	v_lshrrev_b32_e32 v241, 1, v240
	v_add_u32_e32 v241, v241, v70
	v_lshlrev_b32_e32 v241, 11, v241
	v_and_b32_e32 v240, 1, v240
	v_lshl_add_u32 v241, v240, 7, v241
	v_add_u32_e32 v241, 0x800000, v241
	s_lshl_b32 s0, s82, 8
	v_add_u32_e32 v241, s0, v241
	global_load_dword v242, v241, s[16:17]
	global_load_dword v242, v241, s[8:9]
	global_load_dword v242, v241, s[10:11]
